# grid barrier: non-leader workgroups poll the cross-XCD release generation directly instead of waiting for their XCD leader to relay it
# baseline (speedup 1.0000x reference)
.LBB0_47:
	s_or_b64 exec, exec, s[10:11]
	v_cvt_f32_u32_e32 v4, v2
	s_waitcnt vmcnt(0)
	v_readfirstlane_b32 s8, v3
	buffer_inv sc1
	v_sub_u32_e32 v3, 0, v2
	v_rcp_iflag_f32_e32 v4, v4
	v_add_u32_e32 v5, s8, v1
	v_mul_f32_e32 v4, 0x4f7ffffe, v4
	v_cvt_u32_f32_e32 v4, v4
	v_mul_lo_u32 v1, v3, v4
	v_mul_hi_u32 v1, v4, v1
	v_add_u32_e32 v1, v4, v1
	v_mul_hi_u32 v1, v5, v1
	v_mul_lo_u32 v3, v1, v2
	v_sub_u32_e32 v3, v5, v3
	v_add_u32_e32 v4, 1, v1
	v_cmp_ge_u32_e32 vcc, v3, v2
	s_nop 1
	v_cndmask_b32_e32 v1, v1, v4, vcc
	v_sub_u32_e32 v4, v3, v2
	v_cndmask_b32_e32 v3, v3, v4, vcc
	v_add_u32_e32 v4, 1, v1
	v_cmp_ge_u32_e32 vcc, v3, v2
	v_add_u32_e32 v3, 1, v5
	s_nop 0
	v_cndmask_b32_e32 v1, v1, v4, vcc
	v_mul_lo_u32 v4, v2, v1
	v_add_u32_e32 v2, v4, v2
	v_cmp_ne_u32_e32 vcc, v3, v2
	s_and_saveexec_b64 s[8:9], vcc
	s_xor_b64 s[8:9], exec, s[8:9]
	s_cbranch_execz .LBB0_61
	s_waitcnt lgkmcnt(0)
	s_add_u32 s14, s54, 0x6b500
	s_addc_u32 s15, s55, 0
	v_mov_b32_e32 v0, 0
	global_load_dword v0, v0, s[14:15] sc1
	s_waitcnt vmcnt(0)
	v_cmp_eq_u32_e32 vcc, v0, v1
	s_and_saveexec_b64 s[10:11], vcc
	s_cbranch_execz .LBB0_60
	s_add_u32 s12, s54, 0x68200
	s_addc_u32 s13, s55, 0
	s_mov_b32 s26, 1
	s_mov_b64 s[16:17], 0
	v_mov_b32_e32 v0, 0
	s_branch .LBB0_51

.LBB0_202:
	s_or_b64 exec, exec, s[8:9]
	v_cvt_f32_u32_e32 v4, v2
	s_waitcnt vmcnt(0)
	v_readfirstlane_b32 s6, v3
	buffer_inv sc1
	v_sub_u32_e32 v3, 0, v2
	v_rcp_iflag_f32_e32 v4, v4
	v_add_u32_e32 v5, s6, v1
	v_mul_f32_e32 v4, 0x4f7ffffe, v4
	v_cvt_u32_f32_e32 v4, v4
	v_mul_lo_u32 v1, v3, v4
	v_mul_hi_u32 v1, v4, v1
	v_add_u32_e32 v1, v4, v1
	v_mul_hi_u32 v1, v5, v1
	v_mul_lo_u32 v3, v1, v2
	v_sub_u32_e32 v3, v5, v3
	v_add_u32_e32 v4, 1, v1
	v_cmp_ge_u32_e32 vcc, v3, v2
	s_nop 1
	v_cndmask_b32_e32 v1, v1, v4, vcc
	v_sub_u32_e32 v4, v3, v2
	v_cndmask_b32_e32 v3, v3, v4, vcc
	v_add_u32_e32 v4, 1, v1
	v_cmp_ge_u32_e32 vcc, v3, v2
	v_add_u32_e32 v3, 1, v5
	s_nop 0
	v_cndmask_b32_e32 v1, v1, v4, vcc
	v_mul_lo_u32 v4, v2, v1
	v_add_u32_e32 v2, v4, v2
	v_cmp_ne_u32_e32 vcc, v3, v2
	s_and_saveexec_b64 s[6:7], vcc
	s_xor_b64 s[6:7], exec, s[6:7]
	s_cbranch_execz .LBB0_216
	s_waitcnt lgkmcnt(0)
	s_add_u32 s12, s54, 0x6b500
	s_addc_u32 s13, s55, 0
	v_mov_b32_e32 v0, 0
	global_load_dword v0, v0, s[12:13] sc1
	s_waitcnt vmcnt(0)
	v_cmp_eq_u32_e32 vcc, v0, v1
	s_and_saveexec_b64 s[8:9], vcc
	s_cbranch_execz .LBB0_215
	s_add_u32 s10, s54, 0x68200
	s_addc_u32 s11, s55, 0
	s_mov_b32 s24, 1
	s_mov_b64 s[14:15], 0
	v_mov_b32_e32 v0, 0
	s_branch .LBB0_206

.LBB0_1051:
	s_or_b64 exec, exec, s[6:7]
	v_cvt_f32_u32_e32 v4, v2
	s_waitcnt vmcnt(0)
	v_readfirstlane_b32 s4, v3
	buffer_inv sc1
	v_sub_u32_e32 v3, 0, v2
	v_rcp_iflag_f32_e32 v4, v4
	v_add_u32_e32 v5, s4, v1
	v_mul_f32_e32 v4, 0x4f7ffffe, v4
	v_cvt_u32_f32_e32 v4, v4
	v_mul_lo_u32 v1, v3, v4
	v_mul_hi_u32 v1, v4, v1
	v_add_u32_e32 v1, v4, v1
	v_mul_hi_u32 v1, v5, v1
	v_mul_lo_u32 v3, v1, v2
	v_sub_u32_e32 v3, v5, v3
	v_add_u32_e32 v4, 1, v1
	v_cmp_ge_u32_e32 vcc, v3, v2
	s_nop 1
	v_cndmask_b32_e32 v1, v1, v4, vcc
	v_sub_u32_e32 v4, v3, v2
	v_cndmask_b32_e32 v3, v3, v4, vcc
	v_add_u32_e32 v4, 1, v1
	v_cmp_ge_u32_e32 vcc, v3, v2
	v_add_u32_e32 v3, 1, v5
	s_nop 0
	v_cndmask_b32_e32 v1, v1, v4, vcc
	v_mul_lo_u32 v4, v2, v1
	v_add_u32_e32 v2, v4, v2
	v_cmp_ne_u32_e32 vcc, v3, v2
	s_and_saveexec_b64 s[4:5], vcc
	s_xor_b64 s[4:5], exec, s[4:5]
	s_cbranch_execz .LBB0_1065
	s_waitcnt lgkmcnt(0)
	s_add_u32 s10, s54, 0x6b500
	s_addc_u32 s11, s55, 0
	v_mov_b32_e32 v0, 0
	global_load_dword v0, v0, s[10:11] sc1
	s_waitcnt vmcnt(0)
	v_cmp_eq_u32_e32 vcc, v0, v1
	s_and_saveexec_b64 s[6:7], vcc
	s_cbranch_execz .LBB0_1064
	s_add_u32 s8, s54, 0x68200
	s_addc_u32 s9, s55, 0
	s_mov_b32 s22, 1
	s_mov_b64 s[12:13], 0
	v_mov_b32_e32 v0, 0
	s_branch .LBB0_1055
